# GEMM main loop: per-iteration pointer advances moved off the loop tail into four m0 wait-state slots of load segments 2 and 4
# speedup vs baseline: 1.0011x; 1.0011x over previous
; #define PG8_STAGE(bufoff, gbase, voff) do { _Pragma("unroll") for (int _i = 0; _i < 2; ++_i) \
;         __builtin_amdgcn_global_load_lds((const unsigned*)((const char*)(gbase) + (voff)[_i]), (LAS unsigned*)(lds + (bufoff) + ldsw + _i * 8192), 16, 0, 0); } while (0)
; #define PG8_LDA(dst, b, h) do { _Pragma("unroll") for (int m = 0; m < 4; ++m) _Pragma("unroll") for (int k = 0; k < 2; ++k) dst[m][k] = *(const LAS bf16x8*)(lds + PG8_SA(b, h) + aoff + m * 2048 + k * 1024); } while (0)
; #define PG8_LDB(dst, b, h) do { _Pragma("unroll") for (int n = 0; n < 2; ++n) _Pragma("unroll") for (int k = 0; k < 2; ++k) dst[n][k] = *(const LAS bf16x8*)(lds + PG8_SB(b, h) + boff + n * 2048 + k * 1024); } while (0)
; #define PG8_MMA(ai, bj, At, Bt) do { __builtin_amdgcn_s_setprio(1); _Pragma("unroll") for (int m = 0; m < 4; ++m) _Pragma("unroll") for (int n = 0; n < 2; ++n) _Pragma("unroll") for (int k = 0; k < 2; ++k) \
;         acc[ai][bj][m][n] = __builtin_amdgcn_mfma_f32_16x16x32_bf16(Bt[n][k], At[m][k], acc[ai][bj][m][n], 0, 0, 0); __builtin_amdgcn_s_setprio(0); } while (0)
; #define PG8_WAIT_V(n) asm volatile("s_waitcnt vmcnt(" #n ")" ::: "memory")
; #define PG8_WAIT_L(n) asm volatile("s_waitcnt lgkmcnt(" #n ")" ::: "memory")
; #define PG8_BAR __builtin_amdgcn_s_barrier()
; #define PG8_SCHED __builtin_amdgcn_sched_barrier(0)
; __device__ __forceinline__ void gemm_phase(LAS unsigned char* lds, const GemmD g, const Sched& S, const Epi& E) {
;     ...
;         for (int t = 0; t < nt; t += 2) {
;             const bool last = (t == nt - 2);
;             const char* a1 = cA + (size_t)(t + 1) * kstep;
;             const char* a2 = last ? nA : cA + (size_t)(t + 2) * kstep; const char* b2 = last ? nB : cB + (size_t)(t + 2) * kstep;
;             const char* a3 = a2 + kstep; const char* b3 = b2 + kstep;
;             PG8_LDB(B0, 0, 0); PG8_LDB(B1, 0, 1); PG8_SCHED; PG8_LDA(At, 0, 0); PG8_STAGE(PG8_SA(1, 1), a1 + hstepA, voffA);
;             PG8_WAIT_V(8); PG8_WAIT_L(0); PG8_BAR; PG8_MMA(0, 0, At, B0); PG8_MMA(0, 1, At, B1); PG8_BAR; PG8_SCHED;
;             PG8_LDA(At, 0, 1); PG8_STAGE(PG8_SB(0, 0), b2, voffB); PG8_STAGE(PG8_SB(0, 1), b2 + hstepB, voffB); PG8_STAGE(PG8_SA(0, 0), a2, voffA);
;             PG8_WAIT_V(8); PG8_WAIT_L(0); PG8_BAR; PG8_MMA(1, 0, At, B0); PG8_MMA(1, 1, At, B1); PG8_BAR; PG8_SCHED;
.Lprio_done:
	v_add_u32_e32 v240, 0x10000, v160
	v_add_u32_e32 v241, 0x14000, v160
	v_add_u32_e32 v242, 0x18000, v160
	v_add_u32_e32 v243, 0x1c000, v160
	ds_read_b128 v[130:133], v240
	ds_read_b128 v[146:149], v240 offset:1024
	ds_read_b128 v[150:153], v240 offset:2048
	ds_read_b128 v[154:157], v240 offset:3072
	ds_read_b128 v[162:165], v241
	ds_read_b128 v[166:169], v241 offset:1024
	ds_read_b128 v[170:173], v241 offset:2048
	ds_read_b128 v[174:177], v241 offset:3072
	s_add_i32 m0, s31, 0xc000
	ds_read_b128 v[182:185], v161
	ds_read_b128 v[186:189], v161 offset:1024
	ds_read_b128 v[190:193], v161 offset:2048
	ds_read_b128 v[216:219], v161 offset:3072
	ds_read_b128 v[220:223], v161 offset:4096
	ds_read_b128 v[224:227], v161 offset:5120
	ds_read_b128 v[228:231], v161 offset:6144
	ds_read_b128 v[236:239], v161 offset:7168
	global_load_lds_dwordx4 v142, s[8:9]
	s_add_i32 m0, s31, 0xe000
	s_nop 0
	global_load_lds_dwordx4 v144, s[8:9]
	s_add_i32 s92, s26, 2
	s_add_u32 s93, s8, 0x80
	s_addc_u32 s27, s9, 0
	s_add_i32 s22, 0, 0x10000
	s_cmp_eq_u32 s11, s26
	s_cselect_b32 s27, s1, s27
	s_cselect_b32 s26, s0, s93
	s_cselect_b32 vcc_hi, s17, s35
	s_cselect_b32 vcc_lo, s16, s34
	s_add_i32 s23, 0, 0x14000
	s_waitcnt vmcnt(8)
	s_waitcnt lgkmcnt(0)
	s_barrier
	s_waitcnt lgkmcnt(0)
	v_mfma_f32_16x16x32_bf16 v[126:129], v[130:133], v[182:185], 0
	v_mfma_f32_16x16x32_bf16 v[122:125], v[150:153], v[182:185], 0
	v_mfma_f32_16x16x32_bf16 v[110:113], v[130:133], v[190:193], 0
	v_mfma_f32_16x16x32_bf16 v[106:109], v[150:153], v[190:193], 0
	v_mfma_f32_16x16x32_bf16 v[94:97], v[130:133], v[220:223], 0
	v_mfma_f32_16x16x32_bf16 v[90:93], v[150:153], v[220:223], 0
	v_mfma_f32_16x16x32_bf16 v[78:81], v[130:133], v[228:231], 0
	v_mfma_f32_16x16x32_bf16 v[74:77], v[150:153], v[228:231], 0
	v_mfma_f32_16x16x32_bf16 v[126:129], v[146:149], v[186:189], v[126:129]
	v_mfma_f32_16x16x32_bf16 v[122:125], v[154:157], v[186:189], v[122:125]
	v_mfma_f32_16x16x32_bf16 v[110:113], v[146:149], v[216:219], v[110:113]
	v_mfma_f32_16x16x32_bf16 v[106:109], v[154:157], v[216:219], v[106:109]
	v_mfma_f32_16x16x32_bf16 v[94:97], v[146:149], v[224:227], v[94:97]
	v_mfma_f32_16x16x32_bf16 v[90:93], v[154:157], v[224:227], v[90:93]
	v_mfma_f32_16x16x32_bf16 v[78:81], v[146:149], v[236:239], v[78:81]
	v_mfma_f32_16x16x32_bf16 v[74:77], v[154:157], v[236:239], v[74:77]
	v_mfma_f32_16x16x32_bf16 v[118:121], v[162:165], v[182:185], 0
	v_mfma_f32_16x16x32_bf16 v[114:117], v[170:173], v[182:185], 0
	v_mfma_f32_16x16x32_bf16 v[102:105], v[162:165], v[190:193], 0
	v_mfma_f32_16x16x32_bf16 v[98:101], v[170:173], v[190:193], 0
	v_mfma_f32_16x16x32_bf16 v[86:89], v[162:165], v[220:223], 0
	v_mfma_f32_16x16x32_bf16 v[82:85], v[170:173], v[220:223], 0
	v_mfma_f32_16x16x32_bf16 v[70:73], v[162:165], v[228:231], 0
	v_mfma_f32_16x16x32_bf16 v[66:69], v[170:173], v[228:231], 0
	v_mfma_f32_16x16x32_bf16 v[118:121], v[166:169], v[186:189], v[118:121]
	v_mfma_f32_16x16x32_bf16 v[114:117], v[174:177], v[186:189], v[114:117]
	v_mfma_f32_16x16x32_bf16 v[102:105], v[166:169], v[216:219], v[102:105]
	v_mfma_f32_16x16x32_bf16 v[98:101], v[174:177], v[216:219], v[98:101]
	v_mfma_f32_16x16x32_bf16 v[86:89], v[166:169], v[224:227], v[86:89]
	v_mfma_f32_16x16x32_bf16 v[82:85], v[174:177], v[224:227], v[82:85]
	v_mfma_f32_16x16x32_bf16 v[70:73], v[166:169], v[236:239], v[70:73]
	v_mfma_f32_16x16x32_bf16 v[66:69], v[174:177], v[236:239], v[66:69]
	s_barrier
	s_add_i32 s22, s22, s30
	s_mov_b32 m0, s22
	ds_read_b128 v[182:185], v161 offset:16384
	ds_read_b128 v[186:189], v161 offset:17408
	ds_read_b128 v[190:193], v161 offset:18432
	ds_read_b128 v[216:219], v161 offset:19456
	ds_read_b128 v[220:223], v161 offset:20480
	ds_read_b128 v[224:227], v161 offset:21504
	ds_read_b128 v[228:231], v161 offset:22528
	ds_read_b128 v[236:239], v161 offset:23552
	global_load_lds_dwordx4 v136, vcc
	s_add_i32 m0, s22, 0x2000
	s_add_i32 s22, s23, s30
	global_load_lds_dwordx4 v140, vcc
	s_mov_b32 m0, s22
	s_nop 0
	global_load_lds_dwordx4 v253, vcc
	s_add_i32 m0, s22, 0x2000
	s_nop 0
	global_load_lds_dwordx4 v254, vcc
	s_mov_b32 m0, s31
	s_add_u32 s34, s34, 0x100
	global_load_lds_dwordx4 v134, s[26:27]
	s_mov_b32 m0, s14
	s_addc_u32 s35, s35, 0
	global_load_lds_dwordx4 v138, s[26:27]
	s_waitcnt vmcnt(8)
	s_waitcnt lgkmcnt(0)
	s_barrier
	s_waitcnt lgkmcnt(0)
	v_mfma_f32_16x16x32_bf16 v[62:65], v[130:133], v[182:185], 0
	v_mfma_f32_16x16x32_bf16 v[58:61], v[150:153], v[182:185], 0
	v_mfma_f32_16x16x32_bf16 v[46:49], v[130:133], v[190:193], 0
	v_mfma_f32_16x16x32_bf16 v[42:45], v[150:153], v[190:193], 0
	v_mfma_f32_16x16x32_bf16 v[30:33], v[130:133], v[220:223], 0
	v_mfma_f32_16x16x32_bf16 v[26:29], v[150:153], v[220:223], 0
	v_mfma_f32_16x16x32_bf16 v[14:17], v[130:133], v[228:231], 0
	v_mfma_f32_16x16x32_bf16 v[10:13], v[150:153], v[228:231], 0
	v_mfma_f32_16x16x32_bf16 v[62:65], v[146:149], v[186:189], v[62:65]
	v_mfma_f32_16x16x32_bf16 v[58:61], v[154:157], v[186:189], v[58:61]
	v_mfma_f32_16x16x32_bf16 v[46:49], v[146:149], v[216:219], v[46:49]
	v_mfma_f32_16x16x32_bf16 v[42:45], v[154:157], v[216:219], v[42:45]
	v_mfma_f32_16x16x32_bf16 v[30:33], v[146:149], v[224:227], v[30:33]
	v_mfma_f32_16x16x32_bf16 v[26:29], v[154:157], v[224:227], v[26:29]
	v_mfma_f32_16x16x32_bf16 v[14:17], v[146:149], v[236:239], v[14:17]
	v_mfma_f32_16x16x32_bf16 v[10:13], v[154:157], v[236:239], v[10:13]
	v_mfma_f32_16x16x32_bf16 v[54:57], v[162:165], v[182:185], 0
	v_mfma_f32_16x16x32_bf16 v[50:53], v[170:173], v[182:185], 0
	v_mfma_f32_16x16x32_bf16 v[38:41], v[162:165], v[190:193], 0
	v_mfma_f32_16x16x32_bf16 v[34:37], v[170:173], v[190:193], 0
	v_mfma_f32_16x16x32_bf16 v[22:25], v[162:165], v[220:223], 0
	v_mfma_f32_16x16x32_bf16 v[18:21], v[170:173], v[220:223], 0
	v_mfma_f32_16x16x32_bf16 v[6:9], v[162:165], v[228:231], 0
	v_mfma_f32_16x16x32_bf16 v[2:5], v[170:173], v[228:231], 0
	v_mfma_f32_16x16x32_bf16 v[54:57], v[166:169], v[186:189], v[54:57]
	v_mfma_f32_16x16x32_bf16 v[50:53], v[174:177], v[186:189], v[50:53]
	v_mfma_f32_16x16x32_bf16 v[38:41], v[166:169], v[216:219], v[38:41]
	v_mfma_f32_16x16x32_bf16 v[34:37], v[174:177], v[216:219], v[34:37]
	v_mfma_f32_16x16x32_bf16 v[22:25], v[166:169], v[224:227], v[22:25]
	v_mfma_f32_16x16x32_bf16 v[18:21], v[174:177], v[224:227], v[18:21]
	v_mfma_f32_16x16x32_bf16 v[6:9], v[166:169], v[236:239], v[6:9]
	v_mfma_f32_16x16x32_bf16 v[2:5], v[174:177], v[236:239], v[2:5]
	s_barrier
; #define PG8_STAGE(bufoff, gbase, voff) do { _Pragma("unroll") for (int _i = 0; _i < 2; ++_i) \
;         __builtin_amdgcn_global_load_lds((const unsigned*)((const char*)(gbase) + (voff)[_i]), (LAS unsigned*)(lds + (bufoff) + ldsw + _i * 8192), 16, 0, 0); } while (0)
; #define PG8_LDA(dst, b, h) do { _Pragma("unroll") for (int m = 0; m < 4; ++m) _Pragma("unroll") for (int k = 0; k < 2; ++k) dst[m][k] = *(const LAS bf16x8*)(lds + PG8_SA(b, h) + aoff + m * 2048 + k * 1024); } while (0)
; #define PG8_LDB(dst, b, h) do { _Pragma("unroll") for (int n = 0; n < 2; ++n) _Pragma("unroll") for (int k = 0; k < 2; ++k) dst[n][k] = *(const LAS bf16x8*)(lds + PG8_SB(b, h) + boff + n * 2048 + k * 1024); } while (0)
; #define PG8_MMA(ai, bj, At, Bt) do { __builtin_amdgcn_s_setprio(1); _Pragma("unroll") for (int m = 0; m < 4; ++m) _Pragma("unroll") for (int n = 0; n < 2; ++n) _Pragma("unroll") for (int k = 0; k < 2; ++k) \
;         acc[ai][bj][m][n] = __builtin_amdgcn_mfma_f32_16x16x32_bf16(Bt[n][k], At[m][k], acc[ai][bj][m][n], 0, 0, 0); __builtin_amdgcn_s_setprio(0); } while (0)
; #define PG8_WAIT_V(n) asm volatile("s_waitcnt vmcnt(" #n ")" ::: "memory")
; #define PG8_WAIT_L(n) asm volatile("s_waitcnt lgkmcnt(" #n ")" ::: "memory")
; #define PG8_BAR __builtin_amdgcn_s_barrier()
; #define PG8_SCHED __builtin_amdgcn_sched_barrier(0)
; __device__ __forceinline__ void gemm_phase(LAS unsigned char* lds, const GemmD g, const Sched& S, const Epi& E) {
;     ...
;             PG8_LDB(B0, 1, 0); PG8_LDB(B1, 1, 1); PG8_SCHED; PG8_LDA(At, 1, 0); PG8_STAGE(PG8_SA(0, 1), a2 + hstepA, voffA);
;             PG8_WAIT_V(8); PG8_WAIT_L(0); PG8_BAR; PG8_MMA(0, 0, At, B0); PG8_MMA(0, 1, At, B1); PG8_BAR; PG8_SCHED;
;             PG8_LDA(At, 1, 1); PG8_STAGE(PG8_SB(1, 0), b3, voffB); PG8_STAGE(PG8_SB(1, 1), b3 + hstepB, voffB); PG8_STAGE(PG8_SA(1, 0), a3, voffA);
;             PG8_WAIT_V(8); PG8_WAIT_L(0); PG8_BAR; PG8_MMA(1, 0, At, B0); PG8_MMA(1, 1, At, B1); PG8_BAR; PG8_SCHED;
;         }
	s_add_i32 s22, 0, 0x18000
	s_add_i32 s23, 0, 0x1c000
	ds_read_b128 v[130:133], v242
	ds_read_b128 v[146:149], v242 offset:1024
	ds_read_b128 v[150:153], v242 offset:2048
	ds_read_b128 v[154:157], v242 offset:3072
	ds_read_b128 v[162:165], v243
	ds_read_b128 v[166:169], v243 offset:1024
	ds_read_b128 v[170:173], v243 offset:2048
	ds_read_b128 v[174:177], v243 offset:3072
	s_mov_b32 m0, s15
	ds_read_b128 v[182:185], v161 offset:32768
	ds_read_b128 v[186:189], v161 offset:33792
	ds_read_b128 v[190:193], v161 offset:34816
	ds_read_b128 v[216:219], v161 offset:35840
	ds_read_b128 v[220:223], v161 offset:36864
	ds_read_b128 v[224:227], v161 offset:37888
	ds_read_b128 v[228:231], v161 offset:38912
	ds_read_b128 v[236:239], v161 offset:39936
	global_load_lds_dwordx4 v142, s[26:27]
	s_mov_b32 m0, s10
	s_nop 0
	global_load_lds_dwordx4 v144, s[26:27]
	s_waitcnt vmcnt(8)
	s_waitcnt lgkmcnt(0)
	s_barrier
	s_waitcnt lgkmcnt(0)
	v_mfma_f32_16x16x32_bf16 v[126:129], v[130:133], v[182:185], v[126:129]
	v_mfma_f32_16x16x32_bf16 v[122:125], v[150:153], v[182:185], v[122:125]
	v_mfma_f32_16x16x32_bf16 v[110:113], v[130:133], v[190:193], v[110:113]
	v_mfma_f32_16x16x32_bf16 v[106:109], v[150:153], v[190:193], v[106:109]
	v_mfma_f32_16x16x32_bf16 v[94:97], v[130:133], v[220:223], v[94:97]
	v_mfma_f32_16x16x32_bf16 v[90:93], v[150:153], v[220:223], v[90:93]
	v_mfma_f32_16x16x32_bf16 v[78:81], v[130:133], v[228:231], v[78:81]
	v_mfma_f32_16x16x32_bf16 v[74:77], v[150:153], v[228:231], v[74:77]
	v_mfma_f32_16x16x32_bf16 v[126:129], v[146:149], v[186:189], v[126:129]
	v_mfma_f32_16x16x32_bf16 v[122:125], v[154:157], v[186:189], v[122:125]
	v_mfma_f32_16x16x32_bf16 v[110:113], v[146:149], v[216:219], v[110:113]
	v_mfma_f32_16x16x32_bf16 v[106:109], v[154:157], v[216:219], v[106:109]
	v_mfma_f32_16x16x32_bf16 v[94:97], v[146:149], v[224:227], v[94:97]
	v_mfma_f32_16x16x32_bf16 v[90:93], v[154:157], v[224:227], v[90:93]
	v_mfma_f32_16x16x32_bf16 v[78:81], v[146:149], v[236:239], v[78:81]
	v_mfma_f32_16x16x32_bf16 v[74:77], v[154:157], v[236:239], v[74:77]
	v_mfma_f32_16x16x32_bf16 v[118:121], v[162:165], v[182:185], v[118:121]
	v_mfma_f32_16x16x32_bf16 v[114:117], v[170:173], v[182:185], v[114:117]
	v_mfma_f32_16x16x32_bf16 v[102:105], v[162:165], v[190:193], v[102:105]
	v_mfma_f32_16x16x32_bf16 v[98:101], v[170:173], v[190:193], v[98:101]
	v_mfma_f32_16x16x32_bf16 v[86:89], v[162:165], v[220:223], v[86:89]
	v_mfma_f32_16x16x32_bf16 v[82:85], v[170:173], v[220:223], v[82:85]
	v_mfma_f32_16x16x32_bf16 v[70:73], v[162:165], v[228:231], v[70:73]
	v_mfma_f32_16x16x32_bf16 v[66:69], v[170:173], v[228:231], v[66:69]
	v_mfma_f32_16x16x32_bf16 v[118:121], v[166:169], v[186:189], v[118:121]
	v_mfma_f32_16x16x32_bf16 v[114:117], v[174:177], v[186:189], v[114:117]
	v_mfma_f32_16x16x32_bf16 v[102:105], v[166:169], v[216:219], v[102:105]
	v_mfma_f32_16x16x32_bf16 v[98:101], v[174:177], v[216:219], v[98:101]
	v_mfma_f32_16x16x32_bf16 v[86:89], v[166:169], v[224:227], v[86:89]
	v_mfma_f32_16x16x32_bf16 v[82:85], v[174:177], v[224:227], v[82:85]
	v_mfma_f32_16x16x32_bf16 v[70:73], v[166:169], v[236:239], v[70:73]
	v_mfma_f32_16x16x32_bf16 v[66:69], v[174:177], v[236:239], v[66:69]
	s_barrier
	s_add_i32 s22, s22, s30
	s_add_u32 vcc_lo, vcc_lo, s84
	s_addc_u32 vcc_hi, vcc_hi, s85
	s_add_u32 s26, s26, s84
	s_addc_u32 s27, s27, s85
	s_mov_b32 m0, s22
	ds_read_b128 v[182:185], v161 offset:49152
	ds_read_b128 v[186:189], v161 offset:50176
	ds_read_b128 v[190:193], v161 offset:51200
	ds_read_b128 v[216:219], v161 offset:52224
	ds_read_b128 v[220:223], v161 offset:53248
	ds_read_b128 v[224:227], v161 offset:54272
	ds_read_b128 v[228:231], v161 offset:55296
	ds_read_b128 v[236:239], v161 offset:56320
	global_load_lds_dwordx4 v136, vcc
	s_add_i32 m0, s22, 0x2000
	s_add_i32 s22, s23, s30
	global_load_lds_dwordx4 v140, vcc
	s_mov_b32 m0, s22
	s_nop 0
	global_load_lds_dwordx4 v253, vcc
	s_add_i32 m0, s22, 0x2000
	s_nop 0
	global_load_lds_dwordx4 v254, vcc
	s_mov_b32 m0, s18
	s_add_u32 s8, s8, 0x100
	global_load_lds_dwordx4 v134, s[26:27]
	s_mov_b32 m0, s19
	s_addc_u32 s9, s9, 0
	global_load_lds_dwordx4 v138, s[26:27]
	s_waitcnt vmcnt(8)
	s_waitcnt lgkmcnt(0)
	s_barrier
	s_waitcnt lgkmcnt(0)
	v_mfma_f32_16x16x32_bf16 v[62:65], v[130:133], v[182:185], v[62:65]
	v_mfma_f32_16x16x32_bf16 v[58:61], v[150:153], v[182:185], v[58:61]
	v_mfma_f32_16x16x32_bf16 v[46:49], v[130:133], v[190:193], v[46:49]
	v_mfma_f32_16x16x32_bf16 v[42:45], v[150:153], v[190:193], v[42:45]
	v_mfma_f32_16x16x32_bf16 v[30:33], v[130:133], v[220:223], v[30:33]
	v_mfma_f32_16x16x32_bf16 v[26:29], v[150:153], v[220:223], v[26:29]
	v_mfma_f32_16x16x32_bf16 v[14:17], v[130:133], v[228:231], v[14:17]
	v_mfma_f32_16x16x32_bf16 v[10:13], v[150:153], v[228:231], v[10:13]
	v_mfma_f32_16x16x32_bf16 v[62:65], v[146:149], v[186:189], v[62:65]
	v_mfma_f32_16x16x32_bf16 v[58:61], v[154:157], v[186:189], v[58:61]
	v_mfma_f32_16x16x32_bf16 v[46:49], v[146:149], v[216:219], v[46:49]
	v_mfma_f32_16x16x32_bf16 v[42:45], v[154:157], v[216:219], v[42:45]
	v_mfma_f32_16x16x32_bf16 v[30:33], v[146:149], v[224:227], v[30:33]
	v_mfma_f32_16x16x32_bf16 v[26:29], v[154:157], v[224:227], v[26:29]
	v_mfma_f32_16x16x32_bf16 v[14:17], v[146:149], v[236:239], v[14:17]
	v_mfma_f32_16x16x32_bf16 v[10:13], v[154:157], v[236:239], v[10:13]
	v_mfma_f32_16x16x32_bf16 v[54:57], v[162:165], v[182:185], v[54:57]
	v_mfma_f32_16x16x32_bf16 v[50:53], v[170:173], v[182:185], v[50:53]
	v_mfma_f32_16x16x32_bf16 v[38:41], v[162:165], v[190:193], v[38:41]
	v_mfma_f32_16x16x32_bf16 v[34:37], v[170:173], v[190:193], v[34:37]
	v_mfma_f32_16x16x32_bf16 v[22:25], v[162:165], v[220:223], v[22:25]
	v_mfma_f32_16x16x32_bf16 v[18:21], v[170:173], v[220:223], v[18:21]
	v_mfma_f32_16x16x32_bf16 v[6:9], v[162:165], v[228:231], v[6:9]
	v_mfma_f32_16x16x32_bf16 v[2:5], v[170:173], v[228:231], v[2:5]
	v_mfma_f32_16x16x32_bf16 v[54:57], v[166:169], v[186:189], v[54:57]
	v_mfma_f32_16x16x32_bf16 v[50:53], v[174:177], v[186:189], v[50:53]
	v_mfma_f32_16x16x32_bf16 v[38:41], v[166:169], v[216:219], v[38:41]
	v_mfma_f32_16x16x32_bf16 v[34:37], v[174:177], v[216:219], v[34:37]
	v_mfma_f32_16x16x32_bf16 v[22:25], v[166:169], v[224:227], v[22:25]
	v_mfma_f32_16x16x32_bf16 v[18:21], v[174:177], v[224:227], v[18:21]
	v_mfma_f32_16x16x32_bf16 v[6:9], v[166:169], v[236:239], v[6:9]
	v_mfma_f32_16x16x32_bf16 v[2:5], v[174:177], v[236:239], v[2:5]
	s_barrier
	s_cmp_ge_u32 s92, s12
	s_mov_b32 s26, s92
	s_cbranch_scc0 .LBB0_215
	s_branch .Lgemm_after
; #define PG8_STAGE(bufoff, gbase, voff) do { _Pragma("unroll") for (int _i = 0; _i < 2; ++_i) \
;         __builtin_amdgcn_global_load_lds((const unsigned*)((const char*)(gbase) + (voff)[_i]), (LAS unsigned*)(lds + (bufoff) + ldsw + _i * 8192), 16, 0, 0); } while (0)
; #define PG8_LDA(dst, b, h) do { _Pragma("unroll") for (int m = 0; m < 4; ++m) _Pragma("unroll") for (int k = 0; k < 2; ++k) dst[m][k] = *(const LAS bf16x8*)(lds + PG8_SA(b, h) + aoff + m * 2048 + k * 1024); } while (0)
; #define PG8_LDB(dst, b, h) do { _Pragma("unroll") for (int n = 0; n < 2; ++n) _Pragma("unroll") for (int k = 0; k < 2; ++k) dst[n][k] = *(const LAS bf16x8*)(lds + PG8_SB(b, h) + boff + n * 2048 + k * 1024); } while (0)
; #define PG8_MMA(ai, bj, At, Bt) do { __builtin_amdgcn_s_setprio(1); _Pragma("unroll") for (int m = 0; m < 4; ++m) _Pragma("unroll") for (int n = 0; n < 2; ++n) _Pragma("unroll") for (int k = 0; k < 2; ++k) \
;         acc[ai][bj][m][n] = __builtin_amdgcn_mfma_f32_16x16x32_bf16(Bt[n][k], At[m][k], acc[ai][bj][m][n], 0, 0, 0); __builtin_amdgcn_s_setprio(0); } while (0)
; #define PG8_WAIT_V(n) asm volatile("s_waitcnt vmcnt(" #n ")" ::: "memory")
; #define PG8_WAIT_L(n) asm volatile("s_waitcnt lgkmcnt(" #n ")" ::: "memory")
; #define PG8_BAR __builtin_amdgcn_s_barrier()
; #define PG8_SCHED __builtin_amdgcn_sched_barrier(0)
; __device__ __forceinline__ void gemm_phase(LAS unsigned char* lds, const GemmD g, const Sched& S, const Epi& E) {
;     ...
;         for (int t = 0; t < nt; t += 2) {
;             const bool last = (t == nt - 2);
;             const char* a1 = cA + (size_t)(t + 1) * kstep;
;             const char* a2 = last ? nA : cA + (size_t)(t + 2) * kstep; const char* b2 = last ? nB : cB + (size_t)(t + 2) * kstep;
;             const char* a3 = a2 + kstep; const char* b3 = b2 + kstep;
;             PG8_LDB(B0, 0, 0); PG8_LDB(B1, 0, 1); PG8_SCHED; PG8_LDA(At, 0, 0); PG8_STAGE(PG8_SA(1, 1), a1 + hstepA, voffA);
;             PG8_WAIT_V(8); PG8_WAIT_L(0); PG8_BAR; PG8_MMA(0, 0, At, B0); PG8_MMA(0, 1, At, B1); PG8_BAR; PG8_SCHED;
;             PG8_LDA(At, 0, 1); PG8_STAGE(PG8_SB(0, 0), b2, voffB); PG8_STAGE(PG8_SB(0, 1), b2 + hstepB, voffB); PG8_STAGE(PG8_SA(0, 0), a2, voffA);
;             PG8_WAIT_V(8); PG8_WAIT_L(0); PG8_BAR; PG8_MMA(1, 0, At, B0); PG8_MMA(1, 1, At, B1); PG8_BAR; PG8_SCHED;
.LBB0_215:
	ds_read_b128 v[130:133], v240
	ds_read_b128 v[146:149], v240 offset:1024
	ds_read_b128 v[150:153], v240 offset:2048
	ds_read_b128 v[154:157], v240 offset:3072
	ds_read_b128 v[162:165], v241
	ds_read_b128 v[166:169], v241 offset:1024
	ds_read_b128 v[170:173], v241 offset:2048
	ds_read_b128 v[174:177], v241 offset:3072
	s_add_i32 m0, s31, 0xc000
	ds_read_b128 v[182:185], v161
	ds_read_b128 v[186:189], v161 offset:1024
	ds_read_b128 v[190:193], v161 offset:2048
	ds_read_b128 v[216:219], v161 offset:3072
	ds_read_b128 v[220:223], v161 offset:4096
	ds_read_b128 v[224:227], v161 offset:5120
	ds_read_b128 v[228:231], v161 offset:6144
	ds_read_b128 v[236:239], v161 offset:7168
	global_load_lds_dwordx4 v142, s[8:9]
	s_add_i32 m0, s31, 0xe000
	s_nop 0
	global_load_lds_dwordx4 v144, s[8:9]
	s_add_i32 s92, s26, 2
	s_add_u32 s93, s8, 0x80
	s_addc_u32 s27, s9, 0
	s_add_i32 s22, 0, 0x10000
	s_cmp_eq_u32 s11, s26
	s_cselect_b32 s27, s1, s27
	s_cselect_b32 s26, s0, s93
	s_cselect_b32 vcc_hi, s17, s35
	s_cselect_b32 vcc_lo, s16, s34
	s_add_i32 s23, 0, 0x14000
	s_waitcnt vmcnt(8)
	s_waitcnt lgkmcnt(0)
	s_barrier
	s_waitcnt lgkmcnt(0)
	v_mfma_f32_16x16x32_bf16 v[126:129], v[130:133], v[182:185], v[126:129]
	v_mfma_f32_16x16x32_bf16 v[122:125], v[150:153], v[182:185], v[122:125]
	v_mfma_f32_16x16x32_bf16 v[110:113], v[130:133], v[190:193], v[110:113]
	v_mfma_f32_16x16x32_bf16 v[106:109], v[150:153], v[190:193], v[106:109]
	v_mfma_f32_16x16x32_bf16 v[94:97], v[130:133], v[220:223], v[94:97]
	v_mfma_f32_16x16x32_bf16 v[90:93], v[150:153], v[220:223], v[90:93]
	v_mfma_f32_16x16x32_bf16 v[78:81], v[130:133], v[228:231], v[78:81]
	v_mfma_f32_16x16x32_bf16 v[74:77], v[150:153], v[228:231], v[74:77]
	v_mfma_f32_16x16x32_bf16 v[126:129], v[146:149], v[186:189], v[126:129]
	v_mfma_f32_16x16x32_bf16 v[122:125], v[154:157], v[186:189], v[122:125]
	v_mfma_f32_16x16x32_bf16 v[110:113], v[146:149], v[216:219], v[110:113]
	v_mfma_f32_16x16x32_bf16 v[106:109], v[154:157], v[216:219], v[106:109]
	v_mfma_f32_16x16x32_bf16 v[94:97], v[146:149], v[224:227], v[94:97]
	v_mfma_f32_16x16x32_bf16 v[90:93], v[154:157], v[224:227], v[90:93]
	v_mfma_f32_16x16x32_bf16 v[78:81], v[146:149], v[236:239], v[78:81]
	v_mfma_f32_16x16x32_bf16 v[74:77], v[154:157], v[236:239], v[74:77]
	v_mfma_f32_16x16x32_bf16 v[118:121], v[162:165], v[182:185], v[118:121]
	v_mfma_f32_16x16x32_bf16 v[114:117], v[170:173], v[182:185], v[114:117]
	v_mfma_f32_16x16x32_bf16 v[102:105], v[162:165], v[190:193], v[102:105]
	v_mfma_f32_16x16x32_bf16 v[98:101], v[170:173], v[190:193], v[98:101]
	v_mfma_f32_16x16x32_bf16 v[86:89], v[162:165], v[220:223], v[86:89]
	v_mfma_f32_16x16x32_bf16 v[82:85], v[170:173], v[220:223], v[82:85]
	v_mfma_f32_16x16x32_bf16 v[70:73], v[162:165], v[228:231], v[70:73]
	v_mfma_f32_16x16x32_bf16 v[66:69], v[170:173], v[228:231], v[66:69]
	v_mfma_f32_16x16x32_bf16 v[118:121], v[166:169], v[186:189], v[118:121]
	v_mfma_f32_16x16x32_bf16 v[114:117], v[174:177], v[186:189], v[114:117]
	v_mfma_f32_16x16x32_bf16 v[102:105], v[166:169], v[216:219], v[102:105]
	v_mfma_f32_16x16x32_bf16 v[98:101], v[174:177], v[216:219], v[98:101]
	v_mfma_f32_16x16x32_bf16 v[86:89], v[166:169], v[224:227], v[86:89]
	v_mfma_f32_16x16x32_bf16 v[82:85], v[174:177], v[224:227], v[82:85]
	v_mfma_f32_16x16x32_bf16 v[70:73], v[166:169], v[236:239], v[70:73]
	v_mfma_f32_16x16x32_bf16 v[66:69], v[174:177], v[236:239], v[66:69]
	s_barrier
	s_add_i32 s22, s22, s30
	s_mov_b32 m0, s22
	ds_read_b128 v[182:185], v161 offset:16384
	ds_read_b128 v[186:189], v161 offset:17408
	ds_read_b128 v[190:193], v161 offset:18432
	ds_read_b128 v[216:219], v161 offset:19456
	ds_read_b128 v[220:223], v161 offset:20480
	ds_read_b128 v[224:227], v161 offset:21504
	ds_read_b128 v[228:231], v161 offset:22528
	ds_read_b128 v[236:239], v161 offset:23552
	global_load_lds_dwordx4 v136, vcc
	s_add_i32 m0, s22, 0x2000
	s_add_i32 s22, s23, s30
	global_load_lds_dwordx4 v140, vcc
	s_mov_b32 m0, s22
	s_nop 0
	global_load_lds_dwordx4 v253, vcc
	s_add_i32 m0, s22, 0x2000
	s_nop 0
	global_load_lds_dwordx4 v254, vcc
	s_mov_b32 m0, s31
	s_add_u32 s34, s34, 0x100
	global_load_lds_dwordx4 v134, s[26:27]
	s_mov_b32 m0, s14
	s_addc_u32 s35, s35, 0
	global_load_lds_dwordx4 v138, s[26:27]
	s_waitcnt vmcnt(8)
	s_waitcnt lgkmcnt(0)
	s_barrier
	s_waitcnt lgkmcnt(0)
	v_mfma_f32_16x16x32_bf16 v[62:65], v[130:133], v[182:185], v[62:65]
	v_mfma_f32_16x16x32_bf16 v[58:61], v[150:153], v[182:185], v[58:61]
	v_mfma_f32_16x16x32_bf16 v[46:49], v[130:133], v[190:193], v[46:49]
	v_mfma_f32_16x16x32_bf16 v[42:45], v[150:153], v[190:193], v[42:45]
	v_mfma_f32_16x16x32_bf16 v[30:33], v[130:133], v[220:223], v[30:33]
	v_mfma_f32_16x16x32_bf16 v[26:29], v[150:153], v[220:223], v[26:29]
	v_mfma_f32_16x16x32_bf16 v[14:17], v[130:133], v[228:231], v[14:17]
	v_mfma_f32_16x16x32_bf16 v[10:13], v[150:153], v[228:231], v[10:13]
	v_mfma_f32_16x16x32_bf16 v[62:65], v[146:149], v[186:189], v[62:65]
	v_mfma_f32_16x16x32_bf16 v[58:61], v[154:157], v[186:189], v[58:61]
	v_mfma_f32_16x16x32_bf16 v[46:49], v[146:149], v[216:219], v[46:49]
	v_mfma_f32_16x16x32_bf16 v[42:45], v[154:157], v[216:219], v[42:45]
	v_mfma_f32_16x16x32_bf16 v[30:33], v[146:149], v[224:227], v[30:33]
	v_mfma_f32_16x16x32_bf16 v[26:29], v[154:157], v[224:227], v[26:29]
	v_mfma_f32_16x16x32_bf16 v[14:17], v[146:149], v[236:239], v[14:17]
	v_mfma_f32_16x16x32_bf16 v[10:13], v[154:157], v[236:239], v[10:13]
	v_mfma_f32_16x16x32_bf16 v[54:57], v[162:165], v[182:185], v[54:57]
	v_mfma_f32_16x16x32_bf16 v[50:53], v[170:173], v[182:185], v[50:53]
	v_mfma_f32_16x16x32_bf16 v[38:41], v[162:165], v[190:193], v[38:41]
	v_mfma_f32_16x16x32_bf16 v[34:37], v[170:173], v[190:193], v[34:37]
	v_mfma_f32_16x16x32_bf16 v[22:25], v[162:165], v[220:223], v[22:25]
	v_mfma_f32_16x16x32_bf16 v[18:21], v[170:173], v[220:223], v[18:21]
	v_mfma_f32_16x16x32_bf16 v[6:9], v[162:165], v[228:231], v[6:9]
	v_mfma_f32_16x16x32_bf16 v[2:5], v[170:173], v[228:231], v[2:5]
	v_mfma_f32_16x16x32_bf16 v[54:57], v[166:169], v[186:189], v[54:57]
	v_mfma_f32_16x16x32_bf16 v[50:53], v[174:177], v[186:189], v[50:53]
	v_mfma_f32_16x16x32_bf16 v[38:41], v[166:169], v[216:219], v[38:41]
	v_mfma_f32_16x16x32_bf16 v[34:37], v[174:177], v[216:219], v[34:37]
	v_mfma_f32_16x16x32_bf16 v[22:25], v[166:169], v[224:227], v[22:25]
	v_mfma_f32_16x16x32_bf16 v[18:21], v[174:177], v[224:227], v[18:21]
	v_mfma_f32_16x16x32_bf16 v[6:9], v[166:169], v[236:239], v[6:9]
	v_mfma_f32_16x16x32_bf16 v[2:5], v[174:177], v[236:239], v[2:5]
	s_barrier
; #define PG8_STAGE(bufoff, gbase, voff) do { _Pragma("unroll") for (int _i = 0; _i < 2; ++_i) \
;         __builtin_amdgcn_global_load_lds((const unsigned*)((const char*)(gbase) + (voff)[_i]), (LAS unsigned*)(lds + (bufoff) + ldsw + _i * 8192), 16, 0, 0); } while (0)
; #define PG8_LDA(dst, b, h) do { _Pragma("unroll") for (int m = 0; m < 4; ++m) _Pragma("unroll") for (int k = 0; k < 2; ++k) dst[m][k] = *(const LAS bf16x8*)(lds + PG8_SA(b, h) + aoff + m * 2048 + k * 1024); } while (0)
; #define PG8_LDB(dst, b, h) do { _Pragma("unroll") for (int n = 0; n < 2; ++n) _Pragma("unroll") for (int k = 0; k < 2; ++k) dst[n][k] = *(const LAS bf16x8*)(lds + PG8_SB(b, h) + boff + n * 2048 + k * 1024); } while (0)
; #define PG8_MMA(ai, bj, At, Bt) do { __builtin_amdgcn_s_setprio(1); _Pragma("unroll") for (int m = 0; m < 4; ++m) _Pragma("unroll") for (int n = 0; n < 2; ++n) _Pragma("unroll") for (int k = 0; k < 2; ++k) \
;         acc[ai][bj][m][n] = __builtin_amdgcn_mfma_f32_16x16x32_bf16(Bt[n][k], At[m][k], acc[ai][bj][m][n], 0, 0, 0); __builtin_amdgcn_s_setprio(0); } while (0)
; #define PG8_WAIT_V(n) asm volatile("s_waitcnt vmcnt(" #n ")" ::: "memory")
; #define PG8_WAIT_L(n) asm volatile("s_waitcnt lgkmcnt(" #n ")" ::: "memory")
; #define PG8_BAR __builtin_amdgcn_s_barrier()
; #define PG8_SCHED __builtin_amdgcn_sched_barrier(0)
; __device__ __forceinline__ void gemm_phase(LAS unsigned char* lds, const GemmD g, const Sched& S, const Epi& E) {
;     ...
;             PG8_LDB(B0, 1, 0); PG8_LDB(B1, 1, 1); PG8_SCHED; PG8_LDA(At, 1, 0); PG8_STAGE(PG8_SA(0, 1), a2 + hstepA, voffA);
;             PG8_WAIT_V(8); PG8_WAIT_L(0); PG8_BAR; PG8_MMA(0, 0, At, B0); PG8_MMA(0, 1, At, B1); PG8_BAR; PG8_SCHED;
;             PG8_LDA(At, 1, 1); PG8_STAGE(PG8_SB(1, 0), b3, voffB); PG8_STAGE(PG8_SB(1, 1), b3 + hstepB, voffB); PG8_STAGE(PG8_SA(1, 0), a3, voffA);
;             PG8_WAIT_V(8); PG8_WAIT_L(0); PG8_BAR; PG8_MMA(1, 0, At, B0); PG8_MMA(1, 1, At, B1); PG8_BAR; PG8_SCHED;
;         }
	s_add_i32 s22, 0, 0x18000
	s_add_i32 s23, 0, 0x1c000
	ds_read_b128 v[130:133], v242
	ds_read_b128 v[146:149], v242 offset:1024
	ds_read_b128 v[150:153], v242 offset:2048
	ds_read_b128 v[154:157], v242 offset:3072
	ds_read_b128 v[162:165], v243
	ds_read_b128 v[166:169], v243 offset:1024
	ds_read_b128 v[170:173], v243 offset:2048
	ds_read_b128 v[174:177], v243 offset:3072
	s_mov_b32 m0, s15
	ds_read_b128 v[182:185], v161 offset:32768
	ds_read_b128 v[186:189], v161 offset:33792
	ds_read_b128 v[190:193], v161 offset:34816
	ds_read_b128 v[216:219], v161 offset:35840
	ds_read_b128 v[220:223], v161 offset:36864
	ds_read_b128 v[224:227], v161 offset:37888
	ds_read_b128 v[228:231], v161 offset:38912
	ds_read_b128 v[236:239], v161 offset:39936
	global_load_lds_dwordx4 v142, s[26:27]
	s_mov_b32 m0, s10
	s_nop 0
	global_load_lds_dwordx4 v144, s[26:27]
	s_waitcnt vmcnt(8)
	s_waitcnt lgkmcnt(0)
	s_barrier
	s_waitcnt lgkmcnt(0)
	v_mfma_f32_16x16x32_bf16 v[126:129], v[130:133], v[182:185], v[126:129]
	v_mfma_f32_16x16x32_bf16 v[122:125], v[150:153], v[182:185], v[122:125]
	v_mfma_f32_16x16x32_bf16 v[110:113], v[130:133], v[190:193], v[110:113]
	v_mfma_f32_16x16x32_bf16 v[106:109], v[150:153], v[190:193], v[106:109]
	v_mfma_f32_16x16x32_bf16 v[94:97], v[130:133], v[220:223], v[94:97]
	v_mfma_f32_16x16x32_bf16 v[90:93], v[150:153], v[220:223], v[90:93]
	v_mfma_f32_16x16x32_bf16 v[78:81], v[130:133], v[228:231], v[78:81]
	v_mfma_f32_16x16x32_bf16 v[74:77], v[150:153], v[228:231], v[74:77]
	v_mfma_f32_16x16x32_bf16 v[126:129], v[146:149], v[186:189], v[126:129]
	v_mfma_f32_16x16x32_bf16 v[122:125], v[154:157], v[186:189], v[122:125]
	v_mfma_f32_16x16x32_bf16 v[110:113], v[146:149], v[216:219], v[110:113]
	v_mfma_f32_16x16x32_bf16 v[106:109], v[154:157], v[216:219], v[106:109]
	v_mfma_f32_16x16x32_bf16 v[94:97], v[146:149], v[224:227], v[94:97]
	v_mfma_f32_16x16x32_bf16 v[90:93], v[154:157], v[224:227], v[90:93]
	v_mfma_f32_16x16x32_bf16 v[78:81], v[146:149], v[236:239], v[78:81]
	v_mfma_f32_16x16x32_bf16 v[74:77], v[154:157], v[236:239], v[74:77]
	v_mfma_f32_16x16x32_bf16 v[118:121], v[162:165], v[182:185], v[118:121]
	v_mfma_f32_16x16x32_bf16 v[114:117], v[170:173], v[182:185], v[114:117]
	v_mfma_f32_16x16x32_bf16 v[102:105], v[162:165], v[190:193], v[102:105]
	v_mfma_f32_16x16x32_bf16 v[98:101], v[170:173], v[190:193], v[98:101]
	v_mfma_f32_16x16x32_bf16 v[86:89], v[162:165], v[220:223], v[86:89]
	v_mfma_f32_16x16x32_bf16 v[82:85], v[170:173], v[220:223], v[82:85]
	v_mfma_f32_16x16x32_bf16 v[70:73], v[162:165], v[228:231], v[70:73]
	v_mfma_f32_16x16x32_bf16 v[66:69], v[170:173], v[228:231], v[66:69]
	v_mfma_f32_16x16x32_bf16 v[118:121], v[166:169], v[186:189], v[118:121]
	v_mfma_f32_16x16x32_bf16 v[114:117], v[174:177], v[186:189], v[114:117]
	v_mfma_f32_16x16x32_bf16 v[102:105], v[166:169], v[216:219], v[102:105]
	v_mfma_f32_16x16x32_bf16 v[98:101], v[174:177], v[216:219], v[98:101]
	v_mfma_f32_16x16x32_bf16 v[86:89], v[166:169], v[224:227], v[86:89]
	v_mfma_f32_16x16x32_bf16 v[82:85], v[174:177], v[224:227], v[82:85]
	v_mfma_f32_16x16x32_bf16 v[70:73], v[166:169], v[236:239], v[70:73]
	v_mfma_f32_16x16x32_bf16 v[66:69], v[174:177], v[236:239], v[66:69]
	s_barrier
	s_add_i32 s22, s22, s30
	s_add_u32 vcc_lo, vcc_lo, s84
	s_addc_u32 vcc_hi, vcc_hi, s85
	s_add_u32 s26, s26, s84
	s_addc_u32 s27, s27, s85
	s_mov_b32 m0, s22
	ds_read_b128 v[182:185], v161 offset:49152
	ds_read_b128 v[186:189], v161 offset:50176
	ds_read_b128 v[190:193], v161 offset:51200
	ds_read_b128 v[216:219], v161 offset:52224
	ds_read_b128 v[220:223], v161 offset:53248
	ds_read_b128 v[224:227], v161 offset:54272
	ds_read_b128 v[228:231], v161 offset:55296
	ds_read_b128 v[236:239], v161 offset:56320
	global_load_lds_dwordx4 v136, vcc
	s_add_i32 m0, s22, 0x2000
	s_add_i32 s22, s23, s30
	global_load_lds_dwordx4 v140, vcc
	s_mov_b32 m0, s22
	s_nop 0
	global_load_lds_dwordx4 v253, vcc
	s_add_i32 m0, s22, 0x2000
	s_nop 0
	global_load_lds_dwordx4 v254, vcc
	s_mov_b32 m0, s18
	s_add_u32 s8, s8, 0x100
	global_load_lds_dwordx4 v134, s[26:27]
	s_mov_b32 m0, s19
	s_addc_u32 s9, s9, 0
	global_load_lds_dwordx4 v138, s[26:27]
	s_waitcnt vmcnt(8)
	s_waitcnt lgkmcnt(0)
	s_barrier
	s_waitcnt lgkmcnt(0)
	v_mfma_f32_16x16x32_bf16 v[62:65], v[130:133], v[182:185], v[62:65]
	v_mfma_f32_16x16x32_bf16 v[58:61], v[150:153], v[182:185], v[58:61]
	v_mfma_f32_16x16x32_bf16 v[46:49], v[130:133], v[190:193], v[46:49]
	v_mfma_f32_16x16x32_bf16 v[42:45], v[150:153], v[190:193], v[42:45]
	v_mfma_f32_16x16x32_bf16 v[30:33], v[130:133], v[220:223], v[30:33]
	v_mfma_f32_16x16x32_bf16 v[26:29], v[150:153], v[220:223], v[26:29]
	v_mfma_f32_16x16x32_bf16 v[14:17], v[130:133], v[228:231], v[14:17]
	v_mfma_f32_16x16x32_bf16 v[10:13], v[150:153], v[228:231], v[10:13]
	v_mfma_f32_16x16x32_bf16 v[62:65], v[146:149], v[186:189], v[62:65]
	v_mfma_f32_16x16x32_bf16 v[58:61], v[154:157], v[186:189], v[58:61]
	v_mfma_f32_16x16x32_bf16 v[46:49], v[146:149], v[216:219], v[46:49]
	v_mfma_f32_16x16x32_bf16 v[42:45], v[154:157], v[216:219], v[42:45]
	v_mfma_f32_16x16x32_bf16 v[30:33], v[146:149], v[224:227], v[30:33]
	v_mfma_f32_16x16x32_bf16 v[26:29], v[154:157], v[224:227], v[26:29]
	v_mfma_f32_16x16x32_bf16 v[14:17], v[146:149], v[236:239], v[14:17]
	v_mfma_f32_16x16x32_bf16 v[10:13], v[154:157], v[236:239], v[10:13]
	v_mfma_f32_16x16x32_bf16 v[54:57], v[162:165], v[182:185], v[54:57]
	v_mfma_f32_16x16x32_bf16 v[50:53], v[170:173], v[182:185], v[50:53]
	v_mfma_f32_16x16x32_bf16 v[38:41], v[162:165], v[190:193], v[38:41]
	v_mfma_f32_16x16x32_bf16 v[34:37], v[170:173], v[190:193], v[34:37]
	v_mfma_f32_16x16x32_bf16 v[22:25], v[162:165], v[220:223], v[22:25]
	v_mfma_f32_16x16x32_bf16 v[18:21], v[170:173], v[220:223], v[18:21]
	v_mfma_f32_16x16x32_bf16 v[6:9], v[162:165], v[228:231], v[6:9]
	v_mfma_f32_16x16x32_bf16 v[2:5], v[170:173], v[228:231], v[2:5]
	v_mfma_f32_16x16x32_bf16 v[54:57], v[166:169], v[186:189], v[54:57]
	v_mfma_f32_16x16x32_bf16 v[50:53], v[174:177], v[186:189], v[50:53]
	v_mfma_f32_16x16x32_bf16 v[38:41], v[166:169], v[216:219], v[38:41]
	v_mfma_f32_16x16x32_bf16 v[34:37], v[174:177], v[216:219], v[34:37]
	v_mfma_f32_16x16x32_bf16 v[22:25], v[166:169], v[224:227], v[22:25]
	v_mfma_f32_16x16x32_bf16 v[18:21], v[174:177], v[224:227], v[18:21]
	v_mfma_f32_16x16x32_bf16 v[6:9], v[166:169], v[236:239], v[6:9]
	v_mfma_f32_16x16x32_bf16 v[2:5], v[174:177], v[236:239], v[2:5]
	s_barrier
	s_cmp_ge_u32 s92, s12
	s_mov_b32 s26, s92
	s_cbranch_scc0 .LBB0_215
